# P2 fused merge: conv_w slice staged once per item in LDS (was 24 L2 loads per chunk), first-token masks skipped when the chunk has none
# speedup vs baseline: 1.0116x; 1.0045x over previous
.Lst_c1:
	v_readlane_b32 s2, v254, 26
	v_readlane_b32 s3, v254, 27
	s_lshl_b32 s13, s23, 11
	v_lshlrev_b32_e32 v58, 2, v171
	v_add_u32_e32 v59, s13, v58
	v_add_u32_e32 v60, 0x2000, v59
	v_add_u32_e32 v61, 0x4000, v59
	v_add_u32_e32 v58, 0x12000, v58
	s_nop 1
	global_load_dword v62, v59, s[2:3]
	global_load_dword v63, v60, s[2:3]
	global_load_dword v64, v61, s[2:3]
	v_add_u32_e32 v130, s12, v161
	v_cmp_lt_i32_e32 vcc, -1, v130
	s_and_saveexec_b64 s[8:9], vcc
	s_cbranch_execz .Lst_s0
	v_lshlrev_b64 v[52:53], 9, v[130:131]
	v_lshl_add_u64 v[54:55], v[14:15], 0, v[52:53]
	v_lshl_add_u64 v[56:57], v[16:17], 0, v[52:53]
	global_load_dwordx4 v[28:31], v[54:55], off
	global_load_dwordx4 v[32:35], v[56:57], off

.Lst_s2:
	s_or_b64 exec, exec, s[8:9]
	v_readlane_b32 s2, v254, 41
	v_readlane_b32 s3, v254, 42
	s_waitcnt vmcnt(6)
	ds_write_b128 v127, v[20:23]
	ds_write_b16 v175, v24 offset:36864
	ds_write_b16_d16_hi v175, v24 offset:37384
	ds_write_b16 v175, v25 offset:37904
	ds_write_b16_d16_hi v175, v25 offset:38424
	ds_write_b16 v175, v26 offset:38944
	ds_write_b16_d16_hi v175, v26 offset:39464
	ds_write_b16 v175, v27 offset:39984
	ds_write_b16_d16_hi v175, v27 offset:40504
	s_waitcnt vmcnt(4)
	ds_write_b128 v164, v[28:31]
	ds_write_b16 v165, v32 offset:36864
	ds_write_b16_d16_hi v165, v32 offset:37384
	ds_write_b16 v165, v33 offset:37904
	ds_write_b16_d16_hi v165, v33 offset:38424
	ds_write_b16 v165, v34 offset:38944
	ds_write_b16_d16_hi v165, v34 offset:39464
	ds_write_b16 v165, v35 offset:39984
	ds_write_b16_d16_hi v165, v35 offset:40504
	s_waitcnt vmcnt(2)
	ds_write_b128 v166, v[36:39]
	ds_write_b16 v175, v40 offset:37120
	ds_write_b16_d16_hi v175, v40 offset:37640
	ds_write_b16 v175, v41 offset:38160
	ds_write_b16_d16_hi v175, v41 offset:38680
	ds_write_b16 v175, v42 offset:39200
	ds_write_b16_d16_hi v175, v42 offset:39720
	ds_write_b16 v175, v43 offset:40240
	ds_write_b16_d16_hi v175, v43 offset:40760
	s_waitcnt vmcnt(0)
	ds_write_b128 v167, v[44:47]
	ds_write_b16 v173, v48 offset:36864
	ds_write_b16_d16_hi v173, v48 offset:37384
	ds_write_b16 v173, v49 offset:37904
	ds_write_b16_d16_hi v173, v49 offset:38424
	ds_write_b16 v173, v50 offset:38944
	ds_write_b16_d16_hi v173, v50 offset:39464
	ds_write_b16 v173, v51 offset:39984
	ds_write_b16_d16_hi v173, v51 offset:40504
	ds_write_b32 v58, v62
	ds_write_b32 v58, v63 offset:2048
	ds_write_b32 v58, v64 offset:4096


	s_and_saveexec_b64 s[8:9], s[2:3]
	s_cbranch_execz .LBB0_720
	v_readlane_b32 s2, v255, 37
	s_nop 1
	v_mov_b32_e32 v0, s2
	ds_write_b32 v0, v131

.LBB0_728:
	s_or_b64 exec, exec, s[12:13]
	v_readfirstlane_b32 s14, v0
	s_cmp_ge_i32 s14, s22
	s_mov_b64 s[12:13], -1
	s_cbranch_scc1 .LBB0_723
	s_cmp_ge_i32 s14, s21
	v_lshlrev_b32_e32 v92, 1, v138
	v_mbcnt_hi_u32_b32 v102, -1, v220
	s_cbranch_scc0 .LBB0_731
	s_sub_i32 s12, s14, s21
	s_and_b32 s15, s12, 3
	s_lshl_b32 s13, s15, 5
	v_or_b32_e32 v0, s13, v154
	s_lshr_b32 s12, s12, 2
	v_ashrrev_i32_e32 v1, 31, v0
	v_readlane_b32 s24, v254, 54
	v_lshlrev_b64 v[84:85], 12, v[0:1]
	v_readlane_b32 s25, v254, 55
	s_add_i32 s12, s12, s23
	v_mov_b32_e32 v93, v131
	v_lshl_add_u64 v[0:1], s[24:25], 0, v[84:85]
	s_lshl_b32 s24, s12, 7
	s_mov_b32 s25, s92
	v_lshl_add_u64 v[0:1], v[0:1], 0, s[24:25]
	v_lshl_add_u64 v[90:91], v[0:1], 0, v[92:93]
	global_load_dwordx4 v[68:71], v[90:91], off
	global_load_dwordx4 v[64:67], v[90:91], off offset:32
	s_add_i32 s93, s15, 1
	v_lshl_or_b32 v4, s93, 5, v136
	v_mad_u32_u24 v94, v4, s16, v129
	ds_read_b128 v[16:19], v94
	ds_read_b128 v[76:79], v94 offset:32
	s_add_i32 s94, s15, 2
	v_lshl_or_b32 v20, s94, 5, v136
	v_mad_u32_u24 v95, v20, s16, v129
	v_or_b32_e32 v2, s13, v136
	s_add_i32 s95, s15, 3
	v_mad_u32_u24 v93, v2, s16, v129
	v_lshl_or_b32 v20, s95, 5, v136
	ds_read_b128 v[0:3], v93
	ds_read_b128 v[72:75], v93 offset:32
	v_mad_u32_u24 v96, v20, s16, v129
	s_mov_b32 s13, s92
	v_readlane_b32 s56, v254, 22
	s_or_b32 s24, s15, 4
	s_lshl_b64 vcc, s[12:13], 2
	v_readlane_b32 s58, v254, 24
	v_readlane_b32 s59, v254, 25
	s_add_u32 vcc_lo, s58, vcc_lo
	s_addc_u32 vcc_hi, s59, vcc_hi
	s_cmp_eq_u32 s15, 3
	v_readlane_b32 s57, v254, 23
	v_readlane_b32 s56, v255, 4
	v_readlane_b32 s57, v255, 5
	v_readlane_b32 s60, v254, 26
	v_readlane_b32 s61, v254, 27
	v_readlane_b32 s62, v254, 28
	v_readlane_b32 s63, v254, 29
	v_readlane_b32 s64, v254, 30
	v_readlane_b32 s65, v254, 31
	v_readlane_b32 s66, v254, 32
	v_readlane_b32 s67, v254, 33
	v_readlane_b32 s68, v254, 34
	v_readlane_b32 s69, v254, 35
	v_readlane_b32 s70, v254, 36
	v_readlane_b32 s71, v254, 37
	s_waitcnt vmcnt(1) lgkmcnt(3)
	v_mfma_f32_32x32x16_bf16 v[48:63], v[16:19], v[68:71], 0
	ds_read_b128 v[16:19], v95
	ds_read_b128 v[80:83], v95 offset:32
	s_waitcnt lgkmcnt(1)
	v_mfma_f32_32x32x16_bf16 v[32:47], v[16:19], v[68:71], 0
	ds_read_b128 v[16:19], v96
	ds_read_b128 v[86:89], v96 offset:32
	s_waitcnt vmcnt(0)
	v_mfma_f32_32x32x16_bf16 v[48:63], v[76:79], v[64:67], v[48:63]
	global_load_dwordx4 v[76:79], v[90:91], off offset:64
	v_mfma_f32_32x32x16_bf16 v[0:15], v[0:3], v[68:71], 0
	v_mfma_f32_32x32x16_bf16 v[0:15], v[72:75], v[64:67], v[0:15]
	global_load_dwordx4 v[72:75], v[90:91], off offset:96
	s_waitcnt lgkmcnt(1)
	v_mfma_f32_32x32x16_bf16 v[16:31], v[16:19], v[68:71], 0
	v_mfma_f32_32x32x16_bf16 v[32:47], v[80:83], v[64:67], v[32:47]
	s_waitcnt lgkmcnt(0)
	v_mfma_f32_32x32x16_bf16 v[16:31], v[86:89], v[64:67], v[16:31]
	ds_read_b128 v[86:89], v93 offset:64
	ds_read_b128 v[80:83], v93 offset:96
	s_waitcnt vmcnt(1) lgkmcnt(1)
	v_mfma_f32_32x32x16_bf16 v[0:15], v[86:89], v[76:79], v[0:15]
	ds_read_b128 v[86:89], v94 offset:64
	ds_read_b128 v[98:101], v94 offset:96
	s_waitcnt lgkmcnt(1)
	v_mfma_f32_32x32x16_bf16 v[48:63], v[86:89], v[76:79], v[48:63]
	ds_read_b128 v[86:89], v95 offset:64
	ds_read_b128 v[104:107], v95 offset:96
	s_waitcnt lgkmcnt(1)
	v_mfma_f32_32x32x16_bf16 v[32:47], v[86:89], v[76:79], v[32:47]
	ds_read_b128 v[86:89], v96 offset:64
	ds_read_b128 v[112:115], v96 offset:96
	global_load_dword v96, v131, vcc
	s_mov_b32 s62, 0x6e80000
	s_mov_b32 s63, 0
	s_mov_b32 s64, 0x4c80000
	s_mov_b32 s65, 0
	s_mov_b32 s66, 0x2a80000
	s_mov_b32 s67, 0
	v_lshl_add_u64 v[190:191], v[90:91], 0, s[62:63]
	global_load_dwordx4 v[222:225], v[190:191], off
	global_load_dwordx4 v[226:229], v[190:191], off offset:32
	global_load_dwordx4 v[230:233], v[190:191], off offset:64
	global_load_dwordx4 v[234:237], v[190:191], off offset:96
	v_lshl_add_u64 v[190:191], v[90:91], 0, s[64:65]
	global_load_dwordx4 v[238:241], v[190:191], off
	global_load_dwordx4 v[242:245], v[190:191], off offset:32
	global_load_dwordx4 v[246:249], v[190:191], off offset:64
	global_load_dwordx4 v[250:253], v[190:191], off offset:96
	v_lshl_add_u64 v[190:191], v[90:91], 0, s[66:67]
	global_load_dwordx4 v[182:185], v[190:191], off
	global_load_dwordx4 v[186:189], v[190:191], off offset:32
	global_load_dwordx4 v[202:205], v[190:191], off offset:64
	global_load_dwordx4 v[206:209], v[190:191], off offset:96
	s_cselect_b64 vcc, -1, 0
	s_or_b64 vcc, s[8:9], vcc
	s_xor_b32 s13, s15, 2
	s_cmp_lt_u32 s13, 2
	s_waitcnt lgkmcnt(1)
	v_mfma_f32_32x32x16_bf16 v[16:31], v[86:89], v[76:79], v[16:31]
	s_waitcnt vmcnt(13)
	v_mfma_f32_32x32x16_bf16 v[48:63], v[98:101], v[72:75], v[48:63]
	v_mfma_f32_32x32x16_bf16 v[32:47], v[104:107], v[72:75], v[32:47]
	s_nop 10
	v_cndmask_b32_e32 v48, v179, v48, vcc
	v_cndmask_b32_e32 v49, v179, v49, vcc
	v_cndmask_b32_e32 v50, v179, v50, vcc
	v_cndmask_b32_e32 v51, v179, v51, vcc
	v_cndmask_b32_e32 v52, v179, v52, vcc
	v_cndmask_b32_e32 v53, v179, v53, vcc
	v_cndmask_b32_e32 v54, v179, v54, vcc
	s_waitcnt lgkmcnt(0)
	v_mfma_f32_32x32x16_bf16 v[16:31], v[112:115], v[72:75], v[16:31]
	v_cndmask_b32_e32 v55, v179, v55, vcc
	v_cndmask_b32_e32 v56, v179, v56, vcc
	v_cndmask_b32_e32 v57, v179, v57, vcc
	v_cndmask_b32_e32 v58, v179, v58, vcc
	v_cndmask_b32_e32 v59, v179, v59, vcc
	v_cndmask_b32_e32 v60, v179, v60, vcc
	v_cndmask_b32_e32 v61, v179, v61, vcc
	v_cndmask_b32_e32 v62, v179, v62, vcc
	v_cndmask_b32_e32 v116, v179, v63, vcc
	s_cselect_b64 vcc, -1, 0
	s_or_b64 vcc, s[8:9], vcc
	s_or_b32 s13, s15, s20
	s_cmp_eq_u32 s13, 0
	v_cndmask_b32_e32 v117, v179, v32, vcc
	v_cndmask_b32_e32 v118, v179, v33, vcc
	v_cndmask_b32_e32 v119, v179, v34, vcc
	v_cndmask_b32_e32 v120, v179, v35, vcc
	v_cndmask_b32_e32 v121, v179, v36, vcc
	v_cndmask_b32_e32 v122, v179, v37, vcc
	v_cndmask_b32_e32 v123, v179, v38, vcc
	v_cndmask_b32_e32 v130, v179, v39, vcc
	v_cndmask_b32_e32 v63, v179, v40, vcc
	v_cndmask_b32_e32 v111, v179, v41, vcc
	v_cndmask_b32_e32 v110, v179, v42, vcc
	v_cndmask_b32_e32 v109, v179, v43, vcc
	v_cndmask_b32_e32 v108, v179, v44, vcc
	v_cndmask_b32_e32 v107, v179, v45, vcc
	v_cndmask_b32_e32 v106, v179, v46, vcc
	v_cndmask_b32_e32 v105, v179, v47, vcc
	s_cselect_b64 vcc, -1, 0
	v_cndmask_b32_e32 v103, v17, v179, vcc
	v_and_b32_e32 v17, 64, v102
	v_cndmask_b32_e32 v104, v16, v179, vcc
	v_xor_b32_e32 v16, 32, v102
	v_add_u32_e32 v17, 64, v17
	v_cndmask_b32_e32 v101, v18, v179, vcc
	v_cndmask_b32_e32 v100, v19, v179, vcc
	v_cndmask_b32_e32 v99, v20, v179, vcc
	v_cndmask_b32_e32 v98, v21, v179, vcc
	v_cndmask_b32_e32 v97, v22, v179, vcc
	v_cndmask_b32_e32 v95, v23, v179, vcc
	v_cndmask_b32_e32 v94, v24, v179, vcc
	v_cndmask_b32_e32 v93, v25, v179, vcc
	v_cndmask_b32_e32 v91, v26, v179, vcc
	v_cndmask_b32_e32 v90, v27, v179, vcc
	v_cndmask_b32_e32 v86, v28, v179, vcc
	v_cndmask_b32_e32 v87, v29, v179, vcc
	v_cndmask_b32_e32 v88, v30, v179, vcc
	v_cndmask_b32_e32 v89, v31, v179, vcc
	v_cmp_lt_i32_e32 vcc, v16, v17
	v_mfma_f32_32x32x16_bf16 v[0:15], v[80:83], v[72:75], v[0:15]
	s_mov_b32 s13, 0x3fb8aa3b
	v_cndmask_b32_e32 v44, v102, v16, vcc
	v_lshl_or_b32 v16, s24, 5, v136
	v_mad_u32_u24 v40, v16, s16, v129
	ds_read_b128 v[16:19], v40
	ds_read_b128 v[32:35], v40 offset:32
	ds_read_b128 v[36:39], v40 offset:64
	ds_read_b128 v[40:43], v40 offset:96
	v_lshlrev_b32_e32 v112, 2, v44
	s_waitcnt lgkmcnt(3)
	v_mfma_f32_32x32x16_bf16 v[16:31], v[16:19], v[68:71], 0
	s_nop 0
	v_cndmask_b32_e64 v0, v179, v0, s[26:27]
	v_cndmask_b32_e64 v1, v179, v1, s[28:29]
	v_max3_f32 v45, v0, s17, v1
	v_cndmask_b32_e64 v2, v179, v2, s[30:31]
	v_cndmask_b32_e64 v3, v179, v3, s[34:35]
	v_cndmask_b32_e64 v4, v179, v4, s[36:37]
	v_cndmask_b32_e64 v5, v179, v5, s[38:39]
	s_waitcnt lgkmcnt(2)
	v_mfma_f32_32x32x16_bf16 v[16:31], v[32:35], v[64:67], v[16:31]
	v_max3_f32 v32, v45, v2, v3
	v_max3_f32 v32, v32, v4, v5
	v_cndmask_b32_e64 v6, v179, v6, s[96:97]
	v_cndmask_b32_e64 v7, v179, v7, s[2:3]
	v_max3_f32 v32, v32, v6, v7
	v_cndmask_b32_e64 v8, v179, v8, s[72:73]
	v_cndmask_b32_e64 v9, v179, v9, s[74:75]
	s_waitcnt lgkmcnt(1)
	v_mfma_f32_32x32x16_bf16 v[16:31], v[36:39], v[76:79], v[16:31]
	v_max3_f32 v32, v32, v8, v9
	v_cndmask_b32_e64 v34, v179, v10, s[76:77]
	v_cndmask_b32_e64 v11, v179, v11, s[78:79]
	v_max3_f32 v10, v32, v34, v11
	v_cndmask_b32_e64 v12, v179, v12, s[80:81]
	v_cndmask_b32_e64 v13, v179, v13, s[82:83]
	v_max3_f32 v10, v10, v12, v13
	s_waitcnt lgkmcnt(0)
	v_mfma_f32_32x32x16_bf16 v[16:31], v[40:43], v[72:75], v[16:31]
	v_cndmask_b32_e64 v14, v179, v14, s[84:85]
	v_cndmask_b32_e64 v15, v179, v15, s[86:87]
	v_max3_f32 v10, v10, v14, v15
	v_max3_f32 v10, v10, v48, v49
	v_max3_f32 v10, v10, v50, v51
	v_max3_f32 v10, v10, v52, v53
	v_max3_f32 v10, v10, v54, v55
	s_nop 4
	v_cndmask_b32_e64 v16, v16, v179, s[56:57]
	v_readlane_b32 s56, v255, 34
	v_readlane_b32 s57, v255, 35
	v_max3_f32 v10, v10, v56, v57
	v_max3_f32 v10, v10, v58, v59
	v_cndmask_b32_e64 v17, v179, v17, s[56:57]
	v_readlane_b32 s56, v255, 8
	v_readlane_b32 s57, v255, 9
	v_max3_f32 v10, v10, v60, v61
	v_max3_f32 v10, v10, v62, v116
	v_cndmask_b32_e64 v18, v18, v179, s[56:57]
	v_readlane_b32 s56, v255, 10
	v_readlane_b32 s57, v255, 11
	v_max3_f32 v10, v10, v117, v118
	v_max3_f32 v10, v10, v119, v120
	v_cndmask_b32_e64 v19, v19, v179, s[56:57]
	v_readlane_b32 s56, v255, 12
	v_readlane_b32 s57, v255, 13
	v_max3_f32 v10, v10, v121, v122
	v_max3_f32 v10, v10, v123, v130
	v_cndmask_b32_e64 v20, v20, v179, s[56:57]
	v_readlane_b32 s56, v255, 14
	v_readlane_b32 s57, v255, 15
	v_max3_f32 v10, v10, v63, v111
	v_max3_f32 v10, v10, v110, v109
	v_cndmask_b32_e64 v21, v21, v179, s[56:57]
	v_readlane_b32 s56, v255, 16
	v_readlane_b32 s57, v255, 17
	v_max3_f32 v10, v10, v108, v107
	v_max3_f32 v10, v10, v106, v105
	v_cndmask_b32_e64 v22, v22, v179, s[56:57]
	v_readlane_b32 s56, v255, 18
	v_readlane_b32 s57, v255, 19
	v_max3_f32 v10, v10, v104, v103
	v_max3_f32 v10, v10, v101, v100
	v_cndmask_b32_e64 v23, v23, v179, s[56:57]
	v_readlane_b32 s56, v255, 20
	v_readlane_b32 s57, v255, 21
	v_max3_f32 v10, v10, v99, v98
	v_max3_f32 v10, v10, v97, v95
	v_cndmask_b32_e64 v24, v24, v179, s[56:57]
	v_readlane_b32 s56, v255, 22
	v_readlane_b32 s57, v255, 23
	v_max3_f32 v10, v10, v94, v93
	v_max3_f32 v10, v10, v91, v90
	v_cndmask_b32_e64 v25, v25, v179, s[56:57]
	v_readlane_b32 s56, v255, 24
	v_readlane_b32 s57, v255, 25
	v_max3_f32 v10, v10, v86, v87
	v_max3_f32 v10, v10, v88, v89
	v_cndmask_b32_e64 v26, v26, v179, s[56:57]
	v_readlane_b32 s56, v255, 26
	v_readlane_b32 s57, v255, 27
	v_max3_f32 v10, v10, v16, v17
	v_max3_f32 v10, v10, v18, v19
	v_cndmask_b32_e64 v27, v27, v179, s[56:57]
	v_readlane_b32 s56, v255, 28
	v_readlane_b32 s57, v255, 29
	v_max3_f32 v10, v10, v20, v21
	v_max3_f32 v10, v10, v22, v23
	v_cndmask_b32_e64 v28, v28, v179, s[56:57]
	v_readlane_b32 s56, v255, 30
	v_readlane_b32 s57, v255, 31
	v_max3_f32 v10, v10, v24, v25
	v_max3_f32 v10, v10, v26, v27
	v_cndmask_b32_e64 v29, v29, v179, s[56:57]
	v_readlane_b32 s56, v255, 32
	v_readlane_b32 s57, v255, 33
	v_max3_f32 v10, v10, v28, v29
	s_waitcnt vmcnt(12)
	v_mul_f32_e32 v33, 0x3fb8aa3b, v96
	v_cndmask_b32_e64 v30, v30, v179, s[56:57]
	v_readlane_b32 s56, v255, 2
	v_readlane_b32 s57, v255, 3
	v_lshl_add_u32 v115, s93, 6, v139
	v_lshl_or_b32 v114, s12, 6, v137
	v_cndmask_b32_e64 v31, v31, v179, s[56:57]
	v_max3_f32 v10, v10, v30, v31
	ds_bpermute_b32 v32, v112, v10
	s_waitcnt lgkmcnt(0)
	v_max_f32_e32 v32, v32, v32
	v_max_f32_e32 v10, v10, v32
	v_mul_f32_e32 v10, 0x3e38aa3b, v10
	v_max_f32_e32 v10, v10, v33
	v_fma_f32 v0, v0, s18, -v10
	v_exp_f32_e32 v0, v0
	v_fma_f32 v1, v1, s18, -v10
	v_exp_f32_e32 v1, v1
	v_fma_f32 v2, v2, s18, -v10
	v_exp_f32_e32 v2, v2
	v_fma_f32 v3, v3, s18, -v10
	v_exp_f32_e32 v3, v3
	v_fma_f32 v4, v4, s18, -v10
	v_add_f32_e32 v32, 0, v0
	v_exp_f32_e32 v4, v4
	v_fma_f32 v5, v5, s18, -v10
	v_add_f32_e32 v32, v1, v32
	v_exp_f32_e32 v5, v5
	v_fma_f32 v6, v6, s18, -v10
	v_add_f32_e32 v32, v2, v32
	v_exp_f32_e32 v6, v6
	v_fma_f32 v7, v7, s18, -v10
	v_add_f32_e32 v32, v3, v32
	v_exp_f32_e32 v7, v7
	v_add_f32_e32 v32, v4, v32
	v_add_f32_e32 v32, v5, v32
	v_add_f32_e32 v32, v6, v32
	v_fma_f32 v8, v8, s18, -v10
	v_add_f32_e32 v36, v7, v32
	v_exp_f32_e32 v32, v8
	v_fma_f32 v8, v9, s18, -v10
	v_exp_f32_e32 v33, v8
	v_fma_f32 v8, v34, s18, -v10
	v_exp_f32_e32 v34, v8
	v_fma_f32 v8, v11, s18, -v10
	v_exp_f32_e32 v35, v8
	v_fma_f32 v9, v12, s18, -v10
	v_add_f32_e32 v8, v32, v36
	v_exp_f32_e32 v36, v9
	v_fma_f32 v9, v13, s18, -v10
	v_add_f32_e32 v8, v33, v8
	v_exp_f32_e32 v37, v9
	v_fma_f32 v9, v14, s18, -v10
	v_add_f32_e32 v8, v34, v8
	v_exp_f32_e32 v38, v9
	v_fma_f32 v9, v15, s18, -v10
	v_add_f32_e32 v8, v35, v8
	v_exp_f32_e32 v40, v9
	v_fma_f32 v9, v48, s18, -v10
	v_add_f32_e32 v8, v36, v8
	v_exp_f32_e32 v39, v9
	v_fma_f32 v9, v49, s18, -v10
	v_add_f32_e32 v8, v37, v8
	v_exp_f32_e32 v41, v9
	v_fma_f32 v9, v50, s18, -v10
	v_add_f32_e32 v8, v38, v8
	v_exp_f32_e32 v42, v9
	v_fma_f32 v9, v51, s18, -v10
	v_add_f32_e32 v8, v40, v8
	v_exp_f32_e32 v43, v9
	v_fma_f32 v9, v52, s18, -v10
	v_add_f32_e32 v8, v39, v8
	v_exp_f32_e32 v44, v9
	v_fma_f32 v9, v53, s18, -v10
	v_add_f32_e32 v8, v41, v8
	v_exp_f32_e32 v45, v9
	v_fma_f32 v9, v54, s18, -v10
	v_add_f32_e32 v8, v42, v8
	v_exp_f32_e32 v46, v9
	v_fma_f32 v9, v55, s18, -v10
	v_add_f32_e32 v8, v43, v8
	v_exp_f32_e32 v48, v9
	v_fma_f32 v9, v56, s18, -v10
	v_add_f32_e32 v8, v44, v8
	v_exp_f32_e32 v47, v9
	v_fma_f32 v9, v57, s18, -v10
	v_add_f32_e32 v8, v45, v8
	v_exp_f32_e32 v49, v9
	v_fma_f32 v9, v58, s18, -v10
	v_add_f32_e32 v8, v46, v8
	v_exp_f32_e32 v50, v9
	v_fma_f32 v9, v59, s18, -v10
	v_add_f32_e32 v8, v48, v8
	v_exp_f32_e32 v51, v9
	v_fma_f32 v9, v60, s18, -v10
	v_add_f32_e32 v8, v47, v8
	v_exp_f32_e32 v52, v9
	v_fma_f32 v9, v61, s18, -v10
	v_add_f32_e32 v8, v49, v8
	v_exp_f32_e32 v53, v9
	v_fma_f32 v9, v62, s18, -v10
	v_add_f32_e32 v8, v50, v8
	v_exp_f32_e32 v54, v9
	v_fma_f32 v9, v116, s18, -v10
	v_add_f32_e32 v8, v51, v8
	v_exp_f32_e32 v56, v9
	v_fma_f32 v9, v117, s18, -v10
	v_add_f32_e32 v8, v52, v8
	v_exp_f32_e32 v55, v9
	v_fma_f32 v9, v118, s18, -v10
	v_add_f32_e32 v8, v53, v8
	v_exp_f32_e32 v57, v9
	v_fma_f32 v9, v119, s18, -v10
	v_add_f32_e32 v8, v54, v8
	v_exp_f32_e32 v58, v9
	v_fma_f32 v9, v120, s18, -v10
	v_add_f32_e32 v8, v56, v8
	v_exp_f32_e32 v59, v9
	v_fma_f32 v9, v121, s18, -v10
	v_add_f32_e32 v8, v55, v8
	v_exp_f32_e32 v60, v9
	v_fma_f32 v9, v122, s18, -v10
	v_add_f32_e32 v8, v57, v8
	v_exp_f32_e32 v61, v9
	v_fma_f32 v9, v123, s18, -v10
	v_add_f32_e32 v8, v58, v8
	v_exp_f32_e32 v62, v9
	v_fma_f32 v9, v130, s18, -v10
	v_add_f32_e32 v8, v59, v8
	v_exp_f32_e32 v64, v9
	v_fma_f32 v9, v63, s18, -v10
	v_add_f32_e32 v8, v60, v8
	v_exp_f32_e32 v63, v9
	v_fma_f32 v9, v111, s18, -v10
	v_add_f32_e32 v8, v61, v8
	v_exp_f32_e32 v65, v9
	v_fma_f32 v9, v110, s18, -v10
	v_add_f32_e32 v8, v62, v8
	v_exp_f32_e32 v66, v9
	v_fma_f32 v9, v109, s18, -v10
	v_add_f32_e32 v8, v64, v8
	v_exp_f32_e32 v67, v9
	v_fma_f32 v9, v108, s18, -v10
	v_add_f32_e32 v8, v63, v8
	v_exp_f32_e32 v68, v9
	v_fma_f32 v9, v107, s18, -v10
	v_add_f32_e32 v8, v65, v8
	v_exp_f32_e32 v69, v9
	v_fma_f32 v9, v106, s18, -v10
	v_add_f32_e32 v8, v66, v8
	v_exp_f32_e32 v70, v9
	v_fma_f32 v9, v105, s18, -v10
	v_add_f32_e32 v8, v67, v8
	v_exp_f32_e32 v72, v9
	v_fma_f32 v9, v104, s18, -v10
	v_add_f32_e32 v8, v68, v8
	v_exp_f32_e32 v71, v9
	v_fma_f32 v9, v103, s18, -v10
	v_add_f32_e32 v8, v69, v8
	v_exp_f32_e32 v73, v9
	v_fma_f32 v9, v101, s18, -v10
	v_add_f32_e32 v8, v70, v8
	v_exp_f32_e32 v74, v9
	v_fma_f32 v9, v100, s18, -v10
	v_add_f32_e32 v8, v72, v8
	v_exp_f32_e32 v75, v9
	v_fma_f32 v9, v99, s18, -v10
	v_add_f32_e32 v8, v71, v8
	v_exp_f32_e32 v76, v9
	v_fma_f32 v9, v98, s18, -v10
	v_add_f32_e32 v8, v73, v8
	v_exp_f32_e32 v77, v9
	v_fma_f32 v9, v97, s18, -v10
	v_add_f32_e32 v8, v74, v8
	v_exp_f32_e32 v78, v9
	v_fma_f32 v9, v95, s18, -v10
	v_add_f32_e32 v8, v75, v8
	v_exp_f32_e32 v80, v9
	v_fma_f32 v9, v94, s18, -v10
	v_add_f32_e32 v8, v76, v8
	v_exp_f32_e32 v79, v9
	v_fma_f32 v9, v93, s18, -v10
	v_add_f32_e32 v8, v77, v8
	v_exp_f32_e32 v81, v9
	v_fma_f32 v9, v91, s18, -v10
	v_add_f32_e32 v8, v78, v8
	v_exp_f32_e32 v82, v9
	v_fma_f32 v9, v90, s18, -v10
	v_add_f32_e32 v8, v80, v8
	v_exp_f32_e32 v83, v9
	v_fma_f32 v9, v86, s18, -v10
	v_add_f32_e32 v8, v79, v8
	v_exp_f32_e32 v86, v9
	v_fma_f32 v9, v87, s18, -v10
	v_add_f32_e32 v8, v81, v8
	v_exp_f32_e32 v87, v9
	v_fma_f32 v9, v88, s18, -v10
	v_add_f32_e32 v8, v82, v8
	v_exp_f32_e32 v88, v9
	v_fma_f32 v9, v89, s18, -v10
	v_add_f32_e32 v8, v83, v8
	v_exp_f32_e32 v90, v9
	v_fma_f32 v9, v16, s18, -v10
	v_add_f32_e32 v8, v86, v8
	v_exp_f32_e32 v89, v9
	v_fma_f32 v9, v17, s18, -v10
	v_add_f32_e32 v8, v87, v8
	v_exp_f32_e32 v91, v9
	v_fma_f32 v9, v18, s18, -v10
	v_add_f32_e32 v8, v88, v8
	v_exp_f32_e32 v93, v9
	v_fma_f32 v9, v19, s18, -v10
	v_add_f32_e32 v8, v90, v8
	v_exp_f32_e32 v94, v9
	v_fma_f32 v9, v20, s18, -v10
	v_add_f32_e32 v8, v89, v8
	v_exp_f32_e32 v95, v9
	v_fma_f32 v9, v21, s18, -v10
	v_add_f32_e32 v8, v91, v8
	v_exp_f32_e32 v97, v9
	v_fma_f32 v9, v22, s18, -v10
	v_add_f32_e32 v8, v93, v8
	v_exp_f32_e32 v98, v9
	v_fma_f32 v9, v23, s18, -v10
	v_add_f32_e32 v8, v94, v8
	v_exp_f32_e32 v100, v9
	v_fma_f32 v9, v24, s18, -v10
	v_add_f32_e32 v8, v95, v8
	v_exp_f32_e32 v99, v9
	v_fma_f32 v9, v25, s18, -v10
	v_add_f32_e32 v8, v97, v8
	v_exp_f32_e32 v101, v9
	v_fma_f32 v9, v26, s18, -v10
	v_add_f32_e32 v8, v98, v8
	v_exp_f32_e32 v103, v9
	v_fma_f32 v9, v27, s18, -v10
	v_add_f32_e32 v8, v100, v8
	v_exp_f32_e32 v104, v9
	v_fma_f32 v9, v28, s18, -v10
	v_add_f32_e32 v8, v99, v8
	v_exp_f32_e32 v105, v9
	v_fma_f32 v9, v29, s18, -v10
	v_add_f32_e32 v8, v101, v8
	v_exp_f32_e32 v106, v9
	v_fma_f32 v9, v30, s18, -v10
	v_add_f32_e32 v8, v103, v8
	v_exp_f32_e32 v107, v9
	v_fma_f32 v9, v31, s18, -v10
	v_add_f32_e32 v8, v104, v8
	v_exp_f32_e32 v108, v9
	v_add_f32_e32 v8, v105, v8
	v_add_f32_e32 v8, v106, v8
	v_add_f32_e32 v8, v107, v8
	v_add_f32_e32 v8, v108, v8
	ds_bpermute_b32 v9, v112, v8
	v_fma_f32 v10, v96, s13, -v10
	v_exp_f32_e32 v10, v10
	v_cvt_pk_bf16_f32 v0, v0, v1
	v_cvt_pk_bf16_f32 v1, v2, v3
	s_waitcnt lgkmcnt(0)
	v_add_f32_e32 v8, v8, v9
	v_add_f32_e32 v96, v10, v8
	v_div_scale_f32 v8, vcc, v96, v96, 1.0
	v_rcp_f32_e32 v9, v8
	v_cvt_pk_bf16_f32 v2, v4, v5
	v_cvt_pk_bf16_f32 v3, v6, v7
	v_cvt_pk_bf16_f32 v32, v32, v33
	v_fma_f32 v10, -v8, v9, 1.0
	v_fmac_f32_e32 v9, v10, v9
	v_div_scale_f32 v10, vcc, 1.0, v96, 1.0
	v_mul_f32_e32 v11, v10, v9
	v_fma_f32 v12, -v8, v11, v10
	v_fmac_f32_e32 v11, v12, v9
	v_fma_f32 v8, -v8, v11, v10
	v_lshl_add_u32 v12, s15, 6, v139
	v_div_fmas_f32 v109, v8, v9, v11
	v_add_u32_e32 v8, v12, v157
	v_add_u32_e32 v110, 0x9000, v8
	ds_read2_b64 v[8:11], v110 offset1:2
	v_add_u32_e32 v4, v12, v158
	v_add_u32_e32 v119, 0x9000, v4
	ds_read2_b64 v[110:113], v110 offset0:4 offset1:6
	s_waitcnt lgkmcnt(1)
	v_mfma_f32_32x32x16_bf16 v[16:31], v[8:11], v[0:3], 0
	ds_read2_b64 v[4:7], v119 offset1:2
	v_cvt_pk_bf16_f32 v33, v34, v35
	v_cvt_pk_bf16_f32 v34, v36, v37
	v_cvt_pk_bf16_f32 v35, v38, v40
	v_cvt_pk_bf16_f32 v36, v39, v41
	v_cvt_pk_bf16_f32 v37, v42, v43
	v_cvt_pk_bf16_f32 v38, v44, v45
	s_waitcnt lgkmcnt(1)
	v_mfma_f32_32x32x16_bf16 v[16:31], v[110:113], v[32:35], v[16:31]
	ds_read2_b64 v[110:113], v119 offset0:4 offset1:6
	v_cvt_pk_bf16_f32 v39, v46, v48
	v_lshl_add_u32 v116, s94, 6, v139
	v_lshl_add_u32 v117, s95, 6, v139
	v_lshl_add_u32 v118, s24, 6, v139
	v_readlane_b32 s12, v254, 52
	v_readlane_b32 s13, v254, 53
	s_waitcnt lgkmcnt(1)
	v_mfma_f32_32x32x16_bf16 v[0:15], v[4:7], v[0:3], 0
	v_lshlrev_b32_e32 v130, 1, v114
	s_waitcnt lgkmcnt(0)
	v_mfma_f32_32x32x16_bf16 v[0:15], v[110:113], v[32:35], v[0:15]
	v_add_u32_e32 v32, v115, v157
	v_add_u32_e32 v40, 0x9000, v32
	ds_read2_b64 v[32:35], v40 offset1:2
	s_waitcnt lgkmcnt(0)
	v_mfma_f32_32x32x16_bf16 v[16:31], v[32:35], v[36:39], v[16:31]
	v_add_u32_e32 v32, v115, v158
	v_add_u32_e32 v41, 0x9000, v32
	ds_read2_b64 v[32:35], v41 offset1:2
	s_waitcnt lgkmcnt(0)
	v_mfma_f32_32x32x16_bf16 v[0:15], v[32:35], v[36:39], v[0:15]
	ds_read2_b64 v[32:35], v40 offset0:4 offset1:6
	v_cvt_pk_bf16_f32 v36, v47, v49
	v_cvt_pk_bf16_f32 v37, v50, v51
	v_cvt_pk_bf16_f32 v38, v52, v53
	v_cvt_pk_bf16_f32 v39, v54, v56
	s_waitcnt lgkmcnt(0)
	s_nop 0
	v_mfma_f32_32x32x16_bf16 v[16:31], v[32:35], v[36:39], v[16:31]
	ds_read2_b64 v[32:35], v41 offset0:4 offset1:6
	s_waitcnt lgkmcnt(0)
	v_mfma_f32_32x32x16_bf16 v[0:15], v[32:35], v[36:39], v[0:15]
	v_add_u32_e32 v32, v116, v157
	v_add_u32_e32 v40, 0x9000, v32
	ds_read2_b64 v[32:35], v40 offset1:2
	v_cvt_pk_bf16_f32 v36, v55, v57
	v_cvt_pk_bf16_f32 v37, v58, v59
	v_cvt_pk_bf16_f32 v38, v60, v61
	v_cvt_pk_bf16_f32 v39, v62, v64
	s_waitcnt lgkmcnt(0)
	s_nop 0
	v_mfma_f32_32x32x16_bf16 v[16:31], v[32:35], v[36:39], v[16:31]
	v_add_u32_e32 v32, v116, v158
	v_add_u32_e32 v41, 0x9000, v32
	ds_read2_b64 v[32:35], v41 offset1:2
	s_waitcnt lgkmcnt(0)
	v_mfma_f32_32x32x16_bf16 v[0:15], v[32:35], v[36:39], v[0:15]
	ds_read2_b64 v[32:35], v40 offset0:4 offset1:6
	v_cvt_pk_bf16_f32 v36, v63, v65
	v_cvt_pk_bf16_f32 v37, v66, v67
	v_cvt_pk_bf16_f32 v38, v68, v69
	v_cvt_pk_bf16_f32 v39, v70, v72
	s_waitcnt lgkmcnt(0)
	s_nop 0
	v_mfma_f32_32x32x16_bf16 v[16:31], v[32:35], v[36:39], v[16:31]
	ds_read2_b64 v[32:35], v41 offset0:4 offset1:6
	s_waitcnt lgkmcnt(0)
	v_mfma_f32_32x32x16_bf16 v[0:15], v[32:35], v[36:39], v[0:15]
	v_add_u32_e32 v32, v117, v157
	v_add_u32_e32 v40, 0x9000, v32
	ds_read2_b64 v[32:35], v40 offset1:2
	v_cvt_pk_bf16_f32 v36, v71, v73
	v_cvt_pk_bf16_f32 v37, v74, v75
	v_cvt_pk_bf16_f32 v38, v76, v77
	v_cvt_pk_bf16_f32 v39, v78, v80
	s_waitcnt lgkmcnt(0)
	s_nop 0
	v_mfma_f32_32x32x16_bf16 v[16:31], v[32:35], v[36:39], v[16:31]
	v_add_u32_e32 v32, v117, v158
	v_add_u32_e32 v41, 0x9000, v32
	ds_read2_b64 v[32:35], v41 offset1:2
	s_waitcnt lgkmcnt(0)
	v_mfma_f32_32x32x16_bf16 v[0:15], v[32:35], v[36:39], v[0:15]
	ds_read2_b64 v[32:35], v40 offset0:4 offset1:6
	v_cvt_pk_bf16_f32 v36, v79, v81
	v_cvt_pk_bf16_f32 v37, v82, v83
	v_cvt_pk_bf16_f32 v38, v86, v87
	v_cvt_pk_bf16_f32 v39, v88, v90
	s_waitcnt lgkmcnt(0)
	s_nop 0
	v_mfma_f32_32x32x16_bf16 v[16:31], v[32:35], v[36:39], v[16:31]
	ds_read2_b64 v[32:35], v41 offset0:4 offset1:6
	s_waitcnt lgkmcnt(0)
	v_mfma_f32_32x32x16_bf16 v[0:15], v[32:35], v[36:39], v[0:15]
	v_add_u32_e32 v32, v118, v157
	v_add_u32_e32 v40, 0x9000, v32
	ds_read2_b64 v[32:35], v40 offset1:2
	v_cvt_pk_bf16_f32 v36, v89, v91
	v_cvt_pk_bf16_f32 v37, v93, v94
	v_cvt_pk_bf16_f32 v38, v95, v97
	v_cvt_pk_bf16_f32 v39, v98, v100
	s_waitcnt lgkmcnt(0)
	s_nop 0
	v_mfma_f32_32x32x16_bf16 v[16:31], v[32:35], v[36:39], v[16:31]
	v_add_u32_e32 v32, v118, v158
	v_add_u32_e32 v41, 0x9000, v32
	ds_read2_b64 v[32:35], v41 offset1:2
	s_waitcnt lgkmcnt(0)
	v_mfma_f32_32x32x16_bf16 v[0:15], v[32:35], v[36:39], v[0:15]
	ds_read2_b64 v[32:35], v40 offset0:4 offset1:6
	v_cvt_pk_bf16_f32 v36, v99, v101
	v_cvt_pk_bf16_f32 v37, v103, v104
	v_cvt_pk_bf16_f32 v38, v105, v106
	v_cvt_pk_bf16_f32 v39, v107, v108
	s_waitcnt lgkmcnt(0)
	s_nop 0
	v_mfma_f32_32x32x16_bf16 v[16:31], v[32:35], v[36:39], v[16:31]
	ds_read2_b64 v[32:35], v41 offset0:4 offset1:6
	s_waitcnt lgkmcnt(0)
	v_mfma_f32_32x32x16_bf16 v[0:15], v[32:35], v[36:39], v[0:15]
	v_div_fixup_f32 v32, v109, v96, 1.0
	v_lshl_add_u64 v[34:35], s[12:13], 0, v[84:85]
	s_nop 6
	v_pk_mul_f32 v[16:17], v[16:17], v[32:33] op_sel_hi:[1,0]
	v_pk_mul_f32 v[18:19], v[18:19], v[32:33] op_sel_hi:[1,0]
	v_pk_mul_f32 v[20:21], v[20:21], v[32:33] op_sel_hi:[1,0]
	v_pk_mul_f32 v[22:23], v[22:23], v[32:33] op_sel_hi:[1,0]
	v_pk_mul_f32 v[24:25], v[24:25], v[32:33] op_sel_hi:[1,0]
	v_pk_mul_f32 v[26:27], v[26:27], v[32:33] op_sel_hi:[1,0]
	v_pk_mul_f32 v[28:29], v[28:29], v[32:33] op_sel_hi:[1,0]
	v_pk_mul_f32 v[30:31], v[30:31], v[32:33] op_sel_hi:[1,0]
	v_and_b32_e32 v152, 32, v102
	v_lshrrev_b32_e32 v152, 2, v152
	v_mov_b32_e32 v153, 0
	v_lshl_add_u64 v[200:201], v[34:35], 0, v[130:131]
	v_pk_mul_f32 v[0:1], v[0:1], v[32:33] op_sel_hi:[1,0]
	v_pk_mul_f32 v[2:3], v[2:3], v[32:33] op_sel_hi:[1,0]
	v_pk_mul_f32 v[4:5], v[4:5], v[32:33] op_sel_hi:[1,0]
	v_pk_mul_f32 v[6:7], v[6:7], v[32:33] op_sel_hi:[1,0]
	v_pk_mul_f32 v[8:9], v[8:9], v[32:33] op_sel_hi:[1,0]
	v_pk_mul_f32 v[10:11], v[10:11], v[32:33] op_sel_hi:[1,0]
	v_pk_mul_f32 v[12:13], v[12:13], v[32:33] op_sel_hi:[1,0]
	v_pk_mul_f32 v[14:15], v[14:15], v[32:33] op_sel_hi:[1,0]
	v_cvt_pk_bf16_f32 v144, v16, v17
	v_cvt_pk_bf16_f32 v145, v18, v19
	v_cvt_pk_bf16_f32 v146, v20, v21
	v_cvt_pk_bf16_f32 v147, v22, v23
	v_cvt_pk_bf16_f32 v148, v24, v25
	v_cvt_pk_bf16_f32 v149, v26, v27
	v_cvt_pk_bf16_f32 v150, v28, v29
	v_cvt_pk_bf16_f32 v151, v30, v31
	v_cvt_pk_bf16_f32 v192, v0, v1
	v_cvt_pk_bf16_f32 v193, v2, v3
	v_cvt_pk_bf16_f32 v194, v4, v5
	v_cvt_pk_bf16_f32 v195, v6, v7
	v_cvt_pk_bf16_f32 v196, v8, v9
	v_cvt_pk_bf16_f32 v197, v10, v11
	v_cvt_pk_bf16_f32 v198, v12, v13
	v_cvt_pk_bf16_f32 v199, v14, v15
	v_lshl_add_u64 v[200:201], v[200:201], 0, v[152:153]
	s_mov_b32 s62, 0x4c80000
	s_mov_b32 s63, 0
	s_mov_b32 s64, 0x4c7e000
	s_mov_b32 s65, 0
	s_mov_b32 s66, 0x6e80000
	s_mov_b32 s67, 0
	s_mov_b32 s68, 0x9080000
	s_mov_b32 s69, 0
	s_lshl_b32 s66, s23, 8
	s_sub_i32 s66, 0x12000, s66
	v_lshl_add_u64 v[96:97], v[200:201], 0, s[62:63]
	v_lshl_add_u64 v[98:99], v[200:201], 0, s[64:65]
	v_add_u32_e32 v100, v130, v152
	v_lshlrev_b32_e32 v100, 1, v100
	v_add_u32_e32 v100, s66, v100
	v_lshrrev_b32_e32 v32, 12, v84
	v_cmp_gt_u32_e64 s[70:71], 1, v32
	v_cmp_gt_u32_e64 s[94:95], 2, v32
	s_cmp_eq_u64 s[94:95], 0
	s_nop 1
	v_permlane32_swap_b32_e32 v144, v146
	v_permlane32_swap_b32_e32 v145, v147
	v_permlane32_swap_b32_e32 v148, v150
	v_permlane32_swap_b32_e32 v149, v151
	v_permlane32_swap_b32_e32 v192, v194
	v_permlane32_swap_b32_e32 v193, v195
	v_permlane32_swap_b32_e32 v196, v198
	v_permlane32_swap_b32_e32 v197, v199
	global_load_dwordx4 v[104:107], v[96:97], off offset:-4096
	global_load_dwordx4 v[0:3], v[98:99], off
	ds_read_b128 v[36:39], v100
	ds_read_b128 v[40:43], v100 offset:16
	ds_read_b128 v[44:47], v100 offset:2048
	ds_read_b128 v[48:51], v100 offset:2064
	ds_read_b128 v[52:55], v100 offset:4096
	ds_read_b128 v[56:59], v100 offset:4112
	global_load_dwordx4 v[108:111], v[96:97], off offset:-4064
	global_load_dwordx4 v[4:7], v[98:99], off offset:32
	ds_read_b128 v[60:63], v100 offset:64
	ds_read_b128 v[64:67], v100 offset:80
	ds_read_b128 v[68:71], v100 offset:2112
	ds_read_b128 v[72:75], v100 offset:2128
	ds_read_b128 v[76:79], v100 offset:4160
	ds_read_b128 v[80:83], v100 offset:4176
	global_load_dwordx4 v[112:115], v[96:97], off offset:-4032
	global_load_dwordx4 v[8:11], v[98:99], off offset:64
	global_load_dwordx4 v[116:119], v[96:97], off offset:-4000
	global_load_dwordx4 v[12:15], v[98:99], off offset:96
	s_waitcnt vmcnt(6) lgkmcnt(6)
	s_cbranch_scc1 .Lcf_nomask0
	v_cndmask_b32_e64 v104, v104, 0, s[70:71]
	v_cndmask_b32_e64 v0, v0, 0, s[94:95]
	v_cndmask_b32_e64 v105, v105, 0, s[70:71]
	v_cndmask_b32_e64 v1, v1, 0, s[94:95]
	v_cndmask_b32_e64 v106, v106, 0, s[70:71]
	v_cndmask_b32_e64 v2, v2, 0, s[94:95]
	v_cndmask_b32_e64 v107, v107, 0, s[70:71]
	v_cndmask_b32_e64 v3, v3, 0, s[94:95]
.Lcf_nomask0:
	v_lshlrev_b32_e32 v88, 16, v0
	v_and_b32_e32 v89, 0xffff0000, v0
	v_lshlrev_b32_e32 v86, 16, v104
	v_and_b32_e32 v87, 0xffff0000, v104
	v_lshlrev_b32_e32 v34, 16, v182
	v_and_b32_e32 v35, 0xffff0000, v182
	v_lshlrev_b32_e32 v32, 16, v238
	v_and_b32_e32 v33, 0xffff0000, v238
	v_lshlrev_b32_e32 v122, 16, v222
	v_and_b32_e32 v123, 0xffff0000, v222
	v_lshlrev_b32_e32 v120, 16, v144
	v_and_b32_e32 v121, 0xffff0000, v144
	v_pk_mul_f32 v[88:89], v[36:37], v[88:89]
	v_pk_fma_f32 v[88:89], v[44:45], v[86:87], v[88:89]
	v_pk_fma_f32 v[88:89], v[52:53], v[34:35], v[88:89]
	v_pk_mul_f32 v[32:33], v[32:33], v[88:89]
	v_pk_fma_f32 v[32:33], v[122:123], v[120:121], v[32:33]
	v_cvt_pk_bf16_f32 v144, v32, v33
	v_lshlrev_b32_e32 v88, 16, v1
	v_and_b32_e32 v89, 0xffff0000, v1
	v_lshlrev_b32_e32 v86, 16, v105
	v_and_b32_e32 v87, 0xffff0000, v105
	v_lshlrev_b32_e32 v34, 16, v183
	v_and_b32_e32 v35, 0xffff0000, v183
	v_lshlrev_b32_e32 v32, 16, v239
	v_and_b32_e32 v33, 0xffff0000, v239
	v_lshlrev_b32_e32 v122, 16, v223
	v_and_b32_e32 v123, 0xffff0000, v223
	v_lshlrev_b32_e32 v120, 16, v145
	v_and_b32_e32 v121, 0xffff0000, v145
	v_pk_mul_f32 v[88:89], v[38:39], v[88:89]
	v_pk_fma_f32 v[88:89], v[46:47], v[86:87], v[88:89]
	v_pk_fma_f32 v[88:89], v[54:55], v[34:35], v[88:89]
	v_pk_mul_f32 v[32:33], v[32:33], v[88:89]
	v_pk_fma_f32 v[32:33], v[122:123], v[120:121], v[32:33]
	v_cvt_pk_bf16_f32 v145, v32, v33
	v_lshlrev_b32_e32 v88, 16, v2
	v_and_b32_e32 v89, 0xffff0000, v2
	v_lshlrev_b32_e32 v86, 16, v106
	v_and_b32_e32 v87, 0xffff0000, v106
	v_lshlrev_b32_e32 v34, 16, v184
	v_and_b32_e32 v35, 0xffff0000, v184
	v_lshlrev_b32_e32 v32, 16, v240
	v_and_b32_e32 v33, 0xffff0000, v240
	v_lshlrev_b32_e32 v122, 16, v224
	v_and_b32_e32 v123, 0xffff0000, v224
	v_lshlrev_b32_e32 v120, 16, v146
	v_and_b32_e32 v121, 0xffff0000, v146
	v_pk_mul_f32 v[88:89], v[40:41], v[88:89]
	v_pk_fma_f32 v[88:89], v[48:49], v[86:87], v[88:89]
	v_pk_fma_f32 v[88:89], v[56:57], v[34:35], v[88:89]
	v_pk_mul_f32 v[32:33], v[32:33], v[88:89]
	v_pk_fma_f32 v[32:33], v[122:123], v[120:121], v[32:33]
	v_cvt_pk_bf16_f32 v146, v32, v33
	v_lshlrev_b32_e32 v88, 16, v3
	v_and_b32_e32 v89, 0xffff0000, v3
	v_lshlrev_b32_e32 v86, 16, v107
	v_and_b32_e32 v87, 0xffff0000, v107
	v_lshlrev_b32_e32 v34, 16, v185
	v_and_b32_e32 v35, 0xffff0000, v185
	v_lshlrev_b32_e32 v32, 16, v241
	v_and_b32_e32 v33, 0xffff0000, v241
	v_lshlrev_b32_e32 v122, 16, v225
	v_and_b32_e32 v123, 0xffff0000, v225
	v_lshlrev_b32_e32 v120, 16, v147
	v_and_b32_e32 v121, 0xffff0000, v147
	v_pk_mul_f32 v[88:89], v[42:43], v[88:89]
	v_pk_fma_f32 v[88:89], v[50:51], v[86:87], v[88:89]
	v_pk_fma_f32 v[88:89], v[58:59], v[34:35], v[88:89]
	v_pk_mul_f32 v[32:33], v[32:33], v[88:89]
	v_pk_fma_f32 v[32:33], v[122:123], v[120:121], v[32:33]
	v_cvt_pk_bf16_f32 v147, v32, v33
	global_store_dwordx4 v[200:201], v[144:147], off
	ds_read_b128 v[36:39], v100 offset:128
	ds_read_b128 v[40:43], v100 offset:144
	ds_read_b128 v[44:47], v100 offset:2176
	ds_read_b128 v[48:51], v100 offset:2192
	ds_read_b128 v[52:55], v100 offset:4224
	ds_read_b128 v[56:59], v100 offset:4240
	s_waitcnt vmcnt(5) lgkmcnt(6)
	s_cbranch_scc1 .Lcf_nomask1
	v_cndmask_b32_e64 v108, v108, 0, s[70:71]
	v_cndmask_b32_e64 v4, v4, 0, s[94:95]
	v_cndmask_b32_e64 v109, v109, 0, s[70:71]
	v_cndmask_b32_e64 v5, v5, 0, s[94:95]
	v_cndmask_b32_e64 v110, v110, 0, s[70:71]
	v_cndmask_b32_e64 v6, v6, 0, s[94:95]
	v_cndmask_b32_e64 v111, v111, 0, s[70:71]
	v_cndmask_b32_e64 v7, v7, 0, s[94:95]
.Lcf_nomask1:
	v_lshlrev_b32_e32 v88, 16, v4
	v_and_b32_e32 v89, 0xffff0000, v4
	v_lshlrev_b32_e32 v86, 16, v108
	v_and_b32_e32 v87, 0xffff0000, v108
	v_lshlrev_b32_e32 v34, 16, v186
	v_and_b32_e32 v35, 0xffff0000, v186
	v_lshlrev_b32_e32 v32, 16, v242
	v_and_b32_e32 v33, 0xffff0000, v242
	v_lshlrev_b32_e32 v122, 16, v226
	v_and_b32_e32 v123, 0xffff0000, v226
	v_lshlrev_b32_e32 v120, 16, v148
	v_and_b32_e32 v121, 0xffff0000, v148
	v_pk_mul_f32 v[88:89], v[60:61], v[88:89]
	v_pk_fma_f32 v[88:89], v[68:69], v[86:87], v[88:89]
	v_pk_fma_f32 v[88:89], v[76:77], v[34:35], v[88:89]
	v_pk_mul_f32 v[32:33], v[32:33], v[88:89]
	v_pk_fma_f32 v[32:33], v[122:123], v[120:121], v[32:33]
	v_cvt_pk_bf16_f32 v148, v32, v33
	v_lshlrev_b32_e32 v88, 16, v5
	v_and_b32_e32 v89, 0xffff0000, v5
	v_lshlrev_b32_e32 v86, 16, v109
	v_and_b32_e32 v87, 0xffff0000, v109
	v_lshlrev_b32_e32 v34, 16, v187
	v_and_b32_e32 v35, 0xffff0000, v187
	v_lshlrev_b32_e32 v32, 16, v243
	v_and_b32_e32 v33, 0xffff0000, v243
	v_lshlrev_b32_e32 v122, 16, v227
	v_and_b32_e32 v123, 0xffff0000, v227
	v_lshlrev_b32_e32 v120, 16, v149
	v_and_b32_e32 v121, 0xffff0000, v149
	v_pk_mul_f32 v[88:89], v[62:63], v[88:89]
	v_pk_fma_f32 v[88:89], v[70:71], v[86:87], v[88:89]
	v_pk_fma_f32 v[88:89], v[78:79], v[34:35], v[88:89]
	v_pk_mul_f32 v[32:33], v[32:33], v[88:89]
	v_pk_fma_f32 v[32:33], v[122:123], v[120:121], v[32:33]
	v_cvt_pk_bf16_f32 v149, v32, v33
	v_lshlrev_b32_e32 v88, 16, v6
	v_and_b32_e32 v89, 0xffff0000, v6
	v_lshlrev_b32_e32 v86, 16, v110
	v_and_b32_e32 v87, 0xffff0000, v110
	v_lshlrev_b32_e32 v34, 16, v188
	v_and_b32_e32 v35, 0xffff0000, v188
	v_lshlrev_b32_e32 v32, 16, v244
	v_and_b32_e32 v33, 0xffff0000, v244
	v_lshlrev_b32_e32 v122, 16, v228
	v_and_b32_e32 v123, 0xffff0000, v228
	v_lshlrev_b32_e32 v120, 16, v150
	v_and_b32_e32 v121, 0xffff0000, v150
	v_pk_mul_f32 v[88:89], v[64:65], v[88:89]
	v_pk_fma_f32 v[88:89], v[72:73], v[86:87], v[88:89]
	v_pk_fma_f32 v[88:89], v[80:81], v[34:35], v[88:89]
	v_pk_mul_f32 v[32:33], v[32:33], v[88:89]
	v_pk_fma_f32 v[32:33], v[122:123], v[120:121], v[32:33]
	v_cvt_pk_bf16_f32 v150, v32, v33
	v_lshlrev_b32_e32 v88, 16, v7
	v_and_b32_e32 v89, 0xffff0000, v7
	v_lshlrev_b32_e32 v86, 16, v111
	v_and_b32_e32 v87, 0xffff0000, v111
	v_lshlrev_b32_e32 v34, 16, v189
	v_and_b32_e32 v35, 0xffff0000, v189
	v_lshlrev_b32_e32 v32, 16, v245
	v_and_b32_e32 v33, 0xffff0000, v245
	v_lshlrev_b32_e32 v122, 16, v229
	v_and_b32_e32 v123, 0xffff0000, v229
	v_lshlrev_b32_e32 v120, 16, v151
	v_and_b32_e32 v121, 0xffff0000, v151
	v_pk_mul_f32 v[88:89], v[66:67], v[88:89]
	v_pk_fma_f32 v[88:89], v[74:75], v[86:87], v[88:89]
	v_pk_fma_f32 v[88:89], v[82:83], v[34:35], v[88:89]
	v_pk_mul_f32 v[32:33], v[32:33], v[88:89]
	v_pk_fma_f32 v[32:33], v[122:123], v[120:121], v[32:33]
	v_cvt_pk_bf16_f32 v151, v32, v33
	global_store_dwordx4 v[200:201], v[148:151], off offset:32
	ds_read_b128 v[60:63], v100 offset:192
	ds_read_b128 v[64:67], v100 offset:208
	ds_read_b128 v[68:71], v100 offset:2240
	ds_read_b128 v[72:75], v100 offset:2256
	ds_read_b128 v[76:79], v100 offset:4288
	ds_read_b128 v[80:83], v100 offset:4304
	s_waitcnt vmcnt(4) lgkmcnt(6)
	s_cbranch_scc1 .Lcf_nomask2
	v_cndmask_b32_e64 v112, v112, 0, s[70:71]
	v_cndmask_b32_e64 v8, v8, 0, s[94:95]
	v_cndmask_b32_e64 v113, v113, 0, s[70:71]
	v_cndmask_b32_e64 v9, v9, 0, s[94:95]
	v_cndmask_b32_e64 v114, v114, 0, s[70:71]
	v_cndmask_b32_e64 v10, v10, 0, s[94:95]
	v_cndmask_b32_e64 v115, v115, 0, s[70:71]
	v_cndmask_b32_e64 v11, v11, 0, s[94:95]
.Lcf_nomask2:
	v_lshlrev_b32_e32 v88, 16, v8
	v_and_b32_e32 v89, 0xffff0000, v8
	v_lshlrev_b32_e32 v86, 16, v112
	v_and_b32_e32 v87, 0xffff0000, v112
	v_lshlrev_b32_e32 v34, 16, v202
	v_and_b32_e32 v35, 0xffff0000, v202
	v_lshlrev_b32_e32 v32, 16, v246
	v_and_b32_e32 v33, 0xffff0000, v246
	v_lshlrev_b32_e32 v122, 16, v230
	v_and_b32_e32 v123, 0xffff0000, v230
	v_lshlrev_b32_e32 v120, 16, v192
	v_and_b32_e32 v121, 0xffff0000, v192
	v_pk_mul_f32 v[88:89], v[36:37], v[88:89]
	v_pk_fma_f32 v[88:89], v[44:45], v[86:87], v[88:89]
	v_pk_fma_f32 v[88:89], v[52:53], v[34:35], v[88:89]
	v_pk_mul_f32 v[32:33], v[32:33], v[88:89]
	v_pk_fma_f32 v[32:33], v[122:123], v[120:121], v[32:33]
	v_cvt_pk_bf16_f32 v192, v32, v33
	v_lshlrev_b32_e32 v88, 16, v9
	v_and_b32_e32 v89, 0xffff0000, v9
	v_lshlrev_b32_e32 v86, 16, v113
	v_and_b32_e32 v87, 0xffff0000, v113
	v_lshlrev_b32_e32 v34, 16, v203
	v_and_b32_e32 v35, 0xffff0000, v203
	v_lshlrev_b32_e32 v32, 16, v247
	v_and_b32_e32 v33, 0xffff0000, v247
	v_lshlrev_b32_e32 v122, 16, v231
	v_and_b32_e32 v123, 0xffff0000, v231
	v_lshlrev_b32_e32 v120, 16, v193
	v_and_b32_e32 v121, 0xffff0000, v193
	v_pk_mul_f32 v[88:89], v[38:39], v[88:89]
	v_pk_fma_f32 v[88:89], v[46:47], v[86:87], v[88:89]
	v_pk_fma_f32 v[88:89], v[54:55], v[34:35], v[88:89]
	v_pk_mul_f32 v[32:33], v[32:33], v[88:89]
	v_pk_fma_f32 v[32:33], v[122:123], v[120:121], v[32:33]
	v_cvt_pk_bf16_f32 v193, v32, v33
	v_lshlrev_b32_e32 v88, 16, v10
	v_and_b32_e32 v89, 0xffff0000, v10
	v_lshlrev_b32_e32 v86, 16, v114
	v_and_b32_e32 v87, 0xffff0000, v114
	v_lshlrev_b32_e32 v34, 16, v204
	v_and_b32_e32 v35, 0xffff0000, v204
	v_lshlrev_b32_e32 v32, 16, v248
	v_and_b32_e32 v33, 0xffff0000, v248
	v_lshlrev_b32_e32 v122, 16, v232
	v_and_b32_e32 v123, 0xffff0000, v232
	v_lshlrev_b32_e32 v120, 16, v194
	v_and_b32_e32 v121, 0xffff0000, v194
	v_pk_mul_f32 v[88:89], v[40:41], v[88:89]
	v_pk_fma_f32 v[88:89], v[48:49], v[86:87], v[88:89]
	v_pk_fma_f32 v[88:89], v[56:57], v[34:35], v[88:89]
	v_pk_mul_f32 v[32:33], v[32:33], v[88:89]
	v_pk_fma_f32 v[32:33], v[122:123], v[120:121], v[32:33]
	v_cvt_pk_bf16_f32 v194, v32, v33
	v_lshlrev_b32_e32 v88, 16, v11
	v_and_b32_e32 v89, 0xffff0000, v11
	v_lshlrev_b32_e32 v86, 16, v115
	v_and_b32_e32 v87, 0xffff0000, v115
	v_lshlrev_b32_e32 v34, 16, v205
	v_and_b32_e32 v35, 0xffff0000, v205
	v_lshlrev_b32_e32 v32, 16, v249
	v_and_b32_e32 v33, 0xffff0000, v249
	v_lshlrev_b32_e32 v122, 16, v233
	v_and_b32_e32 v123, 0xffff0000, v233
	v_lshlrev_b32_e32 v120, 16, v195
	v_and_b32_e32 v121, 0xffff0000, v195
	v_pk_mul_f32 v[88:89], v[42:43], v[88:89]
	v_pk_fma_f32 v[88:89], v[50:51], v[86:87], v[88:89]
	v_pk_fma_f32 v[88:89], v[58:59], v[34:35], v[88:89]
	v_pk_mul_f32 v[32:33], v[32:33], v[88:89]
	v_pk_fma_f32 v[32:33], v[122:123], v[120:121], v[32:33]
	v_cvt_pk_bf16_f32 v195, v32, v33
	global_store_dwordx4 v[200:201], v[192:195], off offset:64
	s_waitcnt vmcnt(3) lgkmcnt(0)
	s_cbranch_scc1 .Lcf_nomask3
	v_cndmask_b32_e64 v116, v116, 0, s[70:71]
	v_cndmask_b32_e64 v12, v12, 0, s[94:95]
	v_cndmask_b32_e64 v117, v117, 0, s[70:71]
	v_cndmask_b32_e64 v13, v13, 0, s[94:95]
	v_cndmask_b32_e64 v118, v118, 0, s[70:71]
	v_cndmask_b32_e64 v14, v14, 0, s[94:95]
	v_cndmask_b32_e64 v119, v119, 0, s[70:71]
	v_cndmask_b32_e64 v15, v15, 0, s[94:95]
.Lcf_nomask3:
	v_lshlrev_b32_e32 v88, 16, v12
	v_and_b32_e32 v89, 0xffff0000, v12
	v_lshlrev_b32_e32 v86, 16, v116
	v_and_b32_e32 v87, 0xffff0000, v116
	v_lshlrev_b32_e32 v34, 16, v206
	v_and_b32_e32 v35, 0xffff0000, v206
	v_lshlrev_b32_e32 v32, 16, v250
	v_and_b32_e32 v33, 0xffff0000, v250
	v_lshlrev_b32_e32 v122, 16, v234
	v_and_b32_e32 v123, 0xffff0000, v234
	v_lshlrev_b32_e32 v120, 16, v196
	v_and_b32_e32 v121, 0xffff0000, v196
	v_pk_mul_f32 v[88:89], v[60:61], v[88:89]
	v_pk_fma_f32 v[88:89], v[68:69], v[86:87], v[88:89]
	v_pk_fma_f32 v[88:89], v[76:77], v[34:35], v[88:89]
	v_pk_mul_f32 v[32:33], v[32:33], v[88:89]
	v_pk_fma_f32 v[32:33], v[122:123], v[120:121], v[32:33]
	v_cvt_pk_bf16_f32 v196, v32, v33
	v_lshlrev_b32_e32 v88, 16, v13
	v_and_b32_e32 v89, 0xffff0000, v13
	v_lshlrev_b32_e32 v86, 16, v117
	v_and_b32_e32 v87, 0xffff0000, v117
	v_lshlrev_b32_e32 v34, 16, v207
	v_and_b32_e32 v35, 0xffff0000, v207
	v_lshlrev_b32_e32 v32, 16, v251
	v_and_b32_e32 v33, 0xffff0000, v251
	v_lshlrev_b32_e32 v122, 16, v235
	v_and_b32_e32 v123, 0xffff0000, v235
	v_lshlrev_b32_e32 v120, 16, v197
	v_and_b32_e32 v121, 0xffff0000, v197
	v_pk_mul_f32 v[88:89], v[62:63], v[88:89]
	v_pk_fma_f32 v[88:89], v[70:71], v[86:87], v[88:89]
	v_pk_fma_f32 v[88:89], v[78:79], v[34:35], v[88:89]
	v_pk_mul_f32 v[32:33], v[32:33], v[88:89]
	v_pk_fma_f32 v[32:33], v[122:123], v[120:121], v[32:33]
	v_cvt_pk_bf16_f32 v197, v32, v33
	v_lshlrev_b32_e32 v88, 16, v14
	v_and_b32_e32 v89, 0xffff0000, v14
	v_lshlrev_b32_e32 v86, 16, v118
	v_and_b32_e32 v87, 0xffff0000, v118
	v_lshlrev_b32_e32 v34, 16, v208
	v_and_b32_e32 v35, 0xffff0000, v208
	v_lshlrev_b32_e32 v32, 16, v252
	v_and_b32_e32 v33, 0xffff0000, v252
	v_lshlrev_b32_e32 v122, 16, v236
	v_and_b32_e32 v123, 0xffff0000, v236
	v_lshlrev_b32_e32 v120, 16, v198
	v_and_b32_e32 v121, 0xffff0000, v198
	v_pk_mul_f32 v[88:89], v[64:65], v[88:89]
	v_pk_fma_f32 v[88:89], v[72:73], v[86:87], v[88:89]
	v_pk_fma_f32 v[88:89], v[80:81], v[34:35], v[88:89]
	v_pk_mul_f32 v[32:33], v[32:33], v[88:89]
	v_pk_fma_f32 v[32:33], v[122:123], v[120:121], v[32:33]
	v_cvt_pk_bf16_f32 v198, v32, v33
	v_lshlrev_b32_e32 v88, 16, v15
	v_and_b32_e32 v89, 0xffff0000, v15
	v_lshlrev_b32_e32 v86, 16, v119
	v_and_b32_e32 v87, 0xffff0000, v119
	v_lshlrev_b32_e32 v34, 16, v209
	v_and_b32_e32 v35, 0xffff0000, v209
	v_lshlrev_b32_e32 v32, 16, v253
	v_and_b32_e32 v33, 0xffff0000, v253
	v_lshlrev_b32_e32 v122, 16, v237
	v_and_b32_e32 v123, 0xffff0000, v237
	v_lshlrev_b32_e32 v120, 16, v199
	v_and_b32_e32 v121, 0xffff0000, v199
	v_pk_mul_f32 v[88:89], v[66:67], v[88:89]
	v_pk_fma_f32 v[88:89], v[74:75], v[86:87], v[88:89]
	v_pk_fma_f32 v[88:89], v[82:83], v[34:35], v[88:89]
	v_pk_mul_f32 v[32:33], v[32:33], v[88:89]
	v_pk_fma_f32 v[32:33], v[122:123], v[120:121], v[32:33]
	v_cvt_pk_bf16_f32 v199, v32, v33
	global_store_dwordx4 v[200:201], v[196:199], off offset:96


	s_mov_b64 s[12:13], 0
